# same as previous best but P9 stagger shortened to 4 s_sleep (margin inside the spare-tile slack)
# speedup vs baseline: 1.0130x; 1.0063x over previous
.LBB0_1199:
	s_or_b64 exec, exec, s[0:1]
	v_mov_b32_e32 v12, v1
	s_waitcnt lgkmcnt(0)
	s_barrier
	s_cmpk_lt_i32 s79, 0x80
	s_cbranch_scc1 .Lp9_nostagger
	s_sleep 127
	s_sleep 127
	s_sleep 127
	s_sleep 127
.Lp9_nostagger:
	s_cmpk_gt_i32 s79, 0x107f
	v_readfirstlane_b32 s1, v12
	s_cbranch_scc1 .LBB0_1215
	v_lshlrev_b32_e32 v2, 4, v12
	v_add_u32_e32 v3, 0x2000, v2
	v_ashrrev_i32_e32 v4, 31, v3
	v_lshrrev_b32_e32 v4, 22, v4
	v_add_u32_e32 v4, v3, v4
	v_ashrrev_i32_e32 v10, 10, v4
	v_mul_i32_i24_e32 v4, 0x400, v10
	v_sub_u32_e32 v3, v3, v4
	v_lshrrev_b32_e32 v4, 4, v3
	v_bitop3_b32 v3, v4, v3, 32 bitop3:0x6c
	v_ashrrev_i32_e32 v4, 31, v3
	v_lshrrev_b32_e32 v4, 26, v4
	v_add_u32_e32 v4, v3, v4
	v_lshlrev_b32_e32 v5, 3, v10
	v_ashrrev_i32_e32 v11, 6, v4
	v_and_b32_e32 v5, -16, v5
	v_add_u32_e32 v5, v11, v5
	v_and_b32_e32 v6, 3, v11
	s_mov_b32 s0, 0xfffe0
	v_lshrrev_b32_e32 v7, 2, v5
	v_lshlrev_b32_e32 v8, 1, v5
	v_and_b32_e32 v4, 0xc0, v4
	v_and_or_b32 v6, v5, s0, v6
	v_and_b32_e32 v7, 4, v7
	v_and_b32_e32 v8, 24, v8
	v_sub_u32_e32 v3, v3, v4
	v_mov_b32_e32 v4, 1
	v_or3_b32 v6, v6, v7, v8
	v_lshlrev_b32_e32 v7, 5, v10
	v_ashrrev_i16_sdwa v3, v4, sext(v3) dst_sel:DWORD dst_unused:UNUSED_PAD src0_sel:DWORD src1_sel:BYTE_0
	v_and_b32_e32 v7, 32, v7
	v_bfe_i32 v13, v3, 0, 16
	v_add_lshl_u32 v3, v7, v13, 1
	v_lshl_add_u32 v148, v6, 12, v3
	v_lshl_add_u32 v150, v5, 12, v3
	v_bfe_i32 v3, v12, 27, 1
	v_lshrrev_b32_e32 v3, 22, v3
	v_add_u32_e32 v3, v2, v3
	v_and_b32_e32 v3, 0xfffffc00, v3
	v_sub_u32_e32 v2, v2, v3
	v_lshrrev_b32_e32 v3, 4, v2
	v_ashrrev_i32_e32 v5, 31, v12
	v_bitop3_b32 v2, v3, v2, 32 bitop3:0x6c
	v_lshrrev_b32_e32 v5, 26, v5
	v_ashrrev_i32_e32 v3, 31, v2
	v_add_u32_e32 v5, v12, v5
	v_lshrrev_b32_e32 v3, 26, v3
	s_waitcnt vmcnt(50)
	v_ashrrev_i32_e32 v15, 6, v5
	v_add_u32_e32 v3, v2, v3
	v_lshlrev_b32_e32 v5, 3, v15
	v_ashrrev_i32_e32 v14, 6, v3
	v_and_b32_e32 v5, -16, v5
	v_add_u32_e32 v5, v14, v5
	v_and_b32_e32 v6, 3, v14
	s_ashr_i32 s34, s79, 31
	v_and_or_b32 v6, v5, s0, v6
	s_lshr_b32 s0, s34, 29
	s_add_i32 s0, s79, s0
	s_ashr_i32 s8, s1, 6
	s_ashr_i32 s2, s0, 3
	s_and_b32 s0, s0, -8
	s_ashr_i32 s16, s1, 8
	s_lshl_b32 s33, s8, 10
	s_sub_i32 s0, s79, s0
	s_cmp_lt_i32 s0, 0
	s_movk_i32 s35, 0x211
	s_cselect_b32 s3, s35, 0x210
	s_mul_i32 s0, s0, s3
	s_add_i32 s0, s0, s2
	s_mul_hi_i32 s2, s0, 0x2e8ba2e9
	s_lshr_b32 s3, s2, 31
	s_ashr_i32 s2, s2, 6
	s_add_i32 s2, s2, s3
	s_lshl_b32 s3, s2, 3
	s_mulk_i32 s2, 0x160
	s_sub_i32 s2, s0, s2
	s_sext_i32_i16 s0, s2
	s_bfe_u32 s0, s0, 0x3001c
	s_add_i32 s6, s2, s0
	s_sext_i32_i16 s0, s6
	s_and_b32 s6, s6, 0xfff8
	s_sub_i32 s2, s2, s6
	s_sext_i32_i16 s2, s2
	v_lshrrev_b32_e32 v7, 2, v5
	v_lshlrev_b32_e32 v8, 1, v5
	v_and_b32_e32 v3, 0xc0, v3
	s_lshr_b32 s0, s0, 3
	s_add_i32 s6, s3, s2
	v_and_b32_e32 v7, 4, v7
	v_and_b32_e32 v8, 24, v8
	v_sub_u32_e32 v2, v2, v3
	s_ashr_i32 s7, s6, 31
	s_bfe_i64 s[18:19], s[0:1], 0x100000
	v_or3_b32 v6, v6, v7, v8
	v_lshlrev_b32_e32 v7, 5, v15
	v_ashrrev_i16_sdwa v2, v4, sext(v2) dst_sel:DWORD dst_unused:UNUSED_PAD src0_sel:DWORD src1_sel:BYTE_0
	s_lshl_b64 s[2:3], s[6:7], 20
	s_lshl_b64 s[18:19], s[18:19], 20
	v_readlane_b32 s20, v240, 23
	v_and_b32_e32 v7, 32, v7
	v_bfe_i32 v16, v2, 0, 16
	v_readlane_b32 s21, v240, 24
	s_add_u32 s28, s20, s18
	v_add_lshl_u32 v2, v7, v16, 1
	s_addc_u32 s29, s21, s19
	s_add_i32 s36, s33, 0
	v_lshl_add_u32 v152, v6, 12, v2
	s_add_i32 m0, s36, 0x10000
	v_lshl_add_u32 v154, v5, 12, v2
	global_load_lds_dwordx4 v152, s[28:29]
	s_add_i32 m0, s36, 0x12000
	s_add_u32 s18, s28, 0x80000
	global_load_lds_dwordx4 v148, s[28:29]
	s_addc_u32 s19, s29, 0
	s_add_i32 m0, s36, 0x14000
	v_mov_b32_e32 v153, 0
	global_load_lds_dwordx4 v152, s[18:19]
	s_add_i32 m0, s36, 0x16000
	s_add_u32 s26, s52, s2
	s_addc_u32 s27, s53, s3
	s_add_i32 s37, s36, 0x2000
	global_load_lds_dwordx4 v148, s[18:19]
	s_mov_b32 m0, s36
	s_add_u32 s2, s26, 0x80000
	global_load_lds_dwordx4 v154, s[26:27]
	s_mov_b32 m0, s37
	s_addc_u32 s3, s27, 0
	s_add_i32 s38, s36, 0x4000
	global_load_lds_dwordx4 v150, s[26:27]
	s_mov_b32 m0, s38
	s_add_i32 s39, s36, 0x6000
	global_load_lds_dwordx4 v154, s[2:3]
	s_mov_b32 m0, s39
	v_mov_b32_e32 v149, v153
	global_load_lds_dwordx4 v150, s[2:3]
	v_mov_b32_e32 v155, v153
	v_mov_b32_e32 v151, v153
	s_cmp_eq_u32 s16, 1
	s_mov_b32 s40, 0
	v_lshl_add_u64 v[8:9], s[28:29], 0, v[152:153]
	v_lshl_add_u64 v[6:7], s[28:29], 0, v[148:149]
	v_lshl_add_u64 v[2:3], s[26:27], 0, v[154:155]
	s_cselect_b64 s[2:3], -1, 0
	s_cmp_lg_u32 s16, 1
	v_lshl_add_u64 v[4:5], s[26:27], 0, v[150:151]
	s_cbranch_scc1 .LBB0_1202
	s_barrier
